# combo26: combo24 + chunk-attention near-tile body also issues all 8 K-fragment LDS reads at the tile top
# speedup vs baseline: 1.0052x; 1.0052x over previous
; #define LAS __attribute__((address_space(3)))
; __device__ __forceinline__ float fast_exp2(float x) { return __builtin_amdgcn_exp2f(x); }
; #define MFMA32(a, b, c) __builtin_amdgcn_mfma_f32_32x32x16_bf16((a), (b), (c), 0, 0, 0)
; template <int TYPE> __device__ __forceinline__ void attn_unit(const AttnCtx& C, int b, int h, int qb, LAS unsigned char* lds, int tid_in, unsigned* counter) {
;     ...
;             if (active) {
;                 f32x16 p0, p1;
;                 const LAS unsigned char* kp = Kb + bo + hi * 1024 + r32 * 16;
; #pragma unroll
;                 for (int d0 = 0; d0 < 4; ++d0) {
;                     const bf16x8 a0 = *(const LAS bf16x8*)(kp + d0 * 2048), a1 = *(const LAS bf16x8*)(kp + d0 * 2048 + 512);
;                     if (d0 == 0) { p0 = MFMA32(a0, qr[0], (TYPE == 1 ? cvec : zvec)); p1 = MFMA32(a1, qr[0], (TYPE == 1 ? cvec : zvec)); }
;                     else { p0 = MFMA32(a0, qr[d0], p0); p1 = MFMA32(a1, qr[d0], p1); }
;                 }
;     ...
;                     } else {
; #pragma unroll
;                         for (int r = 0; r < 16; ++r) { const int c = (r & 3) + 8 * (r >> 2);
;                             int i0 = xi - c; i0 = i0 < -128 ? -128 : (i0 > 128 ? 128 : i0); int i1 = xi - c - 32; i1 = i1 < -128 ? -128 : (i1 > 128 ? 128 : i1);
;                             p0[r] = fast_exp2(p0[r] + relb[i0 + 128]); p1[r] = fast_exp2(p1[r] + relb[i1 + 128]); }
.LBB0_394:
	s_cmp_lt_i32 s11, s13
	s_cselect_b64 s[0:1], -1, 0
	s_cmp_gt_i32 s11, s2
	s_cselect_b64 s[4:5], -1, 0
	s_or_b64 s[0:1], s[0:1], s[4:5]
	s_and_b64 vcc, exec, s[0:1]
	s_cbranch_vccnz .LBB0_385
	s_cmp_lt_i32 s11, s14
	s_cbranch_scc1 .Lt2far_1
	v_add_u32_e32 v40, s16, v139
	ds_read_b128 v[32:35], v40
	ds_read_b128 v[36:39], v40 offset:512
	ds_read_b128 v[44:47], v40 offset:2048
	ds_read_b128 v[48:51], v40 offset:2560
	ds_read_b128 v[52:55], v40 offset:4096
	ds_read_b128 v[56:59], v40 offset:4608
	ds_read_b128 v[60:63], v40 offset:6144
	ds_read_b128 v[146:149], v40 offset:6656
	s_mov_b64 s[4:5], -1
	s_cmp_lt_i32 s11, s14
	s_waitcnt vmcnt(5) lgkmcnt(6)
	v_mfma_f32_32x32x16_bf16 v[80:95], v[32:35], v[104:107], 0
	v_mfma_f32_32x32x16_bf16 v[64:79], v[36:39], v[104:107], 0
	s_waitcnt lgkmcnt(4)
	v_mfma_f32_32x32x16_bf16 v[80:95], v[44:47], v[96:99], v[80:95]
	v_mfma_f32_32x32x16_bf16 v[64:79], v[48:51], v[96:99], v[64:79]
	s_waitcnt lgkmcnt(2)
	v_mfma_f32_32x32x16_bf16 v[80:95], v[52:55], v[100:103], v[80:95]
	v_mfma_f32_32x32x16_bf16 v[64:79], v[56:59], v[100:103], v[64:79]
	s_waitcnt vmcnt(4) lgkmcnt(0)
	v_mfma_f32_32x32x16_bf16 v[80:95], v[60:63], v[108:111], v[80:95]
	v_mfma_f32_32x32x16_bf16 v[64:79], v[146:149], v[108:111], v[64:79]
	s_cbranch_scc1 .LBB0_397
	v_lshl_add_u32 v230, v141, 2, v162
	s_nop 3
	ds_read_b32 v33, v230 offset:236
	ds_read_b32 v40, v230 offset:108
	ds_read_b32 v35, v230 offset:232
	ds_read_b32 v34, v230 offset:104
	ds_read_b32 v37, v230 offset:228
	ds_read_b32 v36, v230 offset:100
	ds_read_b32 v39, v230 offset:224
	ds_read_b32 v38, v230 offset:96
	s_waitcnt lgkmcnt(7)
	v_add_f32_e32 v32, v80, v33
	s_waitcnt lgkmcnt(6)
	v_add_f32_e32 v33, v64, v40
	v_exp_f32_e32 v48, v33
	s_waitcnt lgkmcnt(5)
	v_add_f32_e32 v33, v81, v35
	s_waitcnt lgkmcnt(2)
	v_add_f32_e32 v35, v66, v36
	s_waitcnt lgkmcnt(0)
	v_add_f32_e32 v36, v67, v38
	v_add_f32_e32 v34, v65, v34
	v_exp_f32_e32 v51, v36
	v_exp_f32_e32 v49, v34
	v_add_f32_e32 v34, v82, v37
	v_exp_f32_e32 v50, v35
	v_add_f32_e32 v35, v83, v39
	ds_read_b32 v37, v230 offset:204
	ds_read_b32 v44, v230 offset:76
	ds_read_b32 v39, v230 offset:200
	ds_read_b32 v38, v230 offset:72
	ds_read_b32 v41, v230 offset:196
	ds_read_b32 v40, v230 offset:68
	ds_read_b32 v43, v230 offset:192
	ds_read_b32 v42, v230 offset:64
	s_waitcnt lgkmcnt(7)
	v_add_f32_e32 v36, v84, v37
	s_waitcnt lgkmcnt(6)
	v_add_f32_e32 v37, v68, v44
	v_exp_f32_e32 v52, v37
	s_waitcnt lgkmcnt(5)
	v_add_f32_e32 v37, v85, v39
	s_waitcnt lgkmcnt(2)
	v_add_f32_e32 v39, v70, v40
	s_waitcnt lgkmcnt(0)
	v_add_f32_e32 v40, v71, v42
	v_add_f32_e32 v38, v69, v38
	v_exp_f32_e32 v55, v40
	v_exp_f32_e32 v53, v38
	v_add_f32_e32 v38, v86, v41
	v_exp_f32_e32 v54, v39
	v_add_f32_e32 v39, v87, v43
	ds_read_b32 v41, v230 offset:172
	ds_read_b32 v56, v230 offset:44
	ds_read_b32 v43, v230 offset:168
	ds_read_b32 v42, v230 offset:40
	ds_read_b32 v45, v230 offset:164
	ds_read_b32 v44, v230 offset:36
	ds_read_b32 v47, v230 offset:160
	ds_read_b32 v46, v230 offset:32
	s_waitcnt lgkmcnt(7)
	v_add_f32_e32 v40, v88, v41
	s_waitcnt lgkmcnt(6)
	v_add_f32_e32 v41, v72, v56
	v_exp_f32_e32 v56, v41
	s_waitcnt lgkmcnt(5)
	v_add_f32_e32 v41, v89, v43
	s_waitcnt lgkmcnt(2)
	v_add_f32_e32 v43, v74, v44
	s_waitcnt lgkmcnt(0)
	v_add_f32_e32 v44, v75, v46
	v_add_f32_e32 v42, v73, v42
	v_exp_f32_e32 v59, v44
	v_exp_f32_e32 v57, v42
	v_add_f32_e32 v42, v90, v45
	v_exp_f32_e32 v58, v43
	v_add_f32_e32 v43, v91, v47
	ds_read_b32 v45, v230 offset:140
	ds_read_b32 v142, v230 offset:12
	ds_read_b32 v47, v230 offset:136
	ds_read_b32 v46, v230 offset:8
	ds_read_b32 v143, v230 offset:132
	ds_read_b32 v144, v230 offset:4
	ds_read_b32 v146, v230 offset:128
	ds_read_b32 v63, v230
	s_waitcnt lgkmcnt(7)
	v_add_f32_e32 v44, v92, v45
	s_waitcnt lgkmcnt(6)
	v_add_f32_e32 v45, v76, v142
	v_exp_f32_e32 v60, v45
	s_waitcnt lgkmcnt(5)
	v_add_f32_e32 v45, v93, v47
	s_waitcnt lgkmcnt(4)
	v_add_f32_e32 v46, v77, v46
	s_waitcnt lgkmcnt(2)
	v_add_f32_e32 v47, v78, v144
	v_exp_f32_e32 v61, v46
	v_add_f32_e32 v46, v94, v143
	v_exp_f32_e32 v62, v47
	s_waitcnt lgkmcnt(1)
	v_add_f32_e32 v47, v95, v146
	v_exp_f32_e32 v32, v32
	v_exp_f32_e32 v33, v33
	v_exp_f32_e32 v34, v34
	v_exp_f32_e32 v35, v35
	v_exp_f32_e32 v36, v36
	v_exp_f32_e32 v37, v37
	v_exp_f32_e32 v38, v38
	v_exp_f32_e32 v39, v39
	v_exp_f32_e32 v40, v40
	v_exp_f32_e32 v41, v41
	v_exp_f32_e32 v42, v42
	v_exp_f32_e32 v43, v43
	v_exp_f32_e32 v44, v44
	v_exp_f32_e32 v45, v45
	v_exp_f32_e32 v46, v46
	v_exp_f32_e32 v47, v47
	s_waitcnt lgkmcnt(0)
	v_add_f32_e32 v63, v79, v63
	s_mov_b64 s[4:5], 0

; #define LAS __attribute__((address_space(3)))
; __device__ __forceinline__ float fast_exp2(float x) { return __builtin_amdgcn_exp2f(x); }
; #define MFMA32(a, b, c) __builtin_amdgcn_mfma_f32_32x32x16_bf16((a), (b), (c), 0, 0, 0)
; template <int TYPE> __device__ __forceinline__ void attn_unit(const AttnCtx& C, int b, int h, int qb, LAS unsigned char* lds, int tid_in, unsigned* counter) {
;     ...
;             if (active) {
;                 f32x16 p0, p1;
;                 const LAS unsigned char* kp = Kb + bo + hi * 1024 + r32 * 16;
; #pragma unroll
;                 for (int d0 = 0; d0 < 4; ++d0) {
;                     const bf16x8 a0 = *(const LAS bf16x8*)(kp + d0 * 2048), a1 = *(const LAS bf16x8*)(kp + d0 * 2048 + 512);
;                     if (d0 == 0) { p0 = MFMA32(a0, qr[0], (TYPE == 1 ? cvec : zvec)); p1 = MFMA32(a1, qr[0], (TYPE == 1 ? cvec : zvec)); }
;                     else { p0 = MFMA32(a0, qr[d0], p0); p1 = MFMA32(a1, qr[d0], p1); }
;                 }
;     ...
;                     } else {
; #pragma unroll
;                         for (int r = 0; r < 16; ++r) { const int c = (r & 3) + 8 * (r >> 2);
;                             int i0 = xi - c; i0 = i0 < -128 ? -128 : (i0 > 128 ? 128 : i0); int i1 = xi - c - 32; i1 = i1 < -128 ? -128 : (i1 > 128 ? 128 : i1);
;                             p0[r] = fast_exp2(p0[r] + relb[i0 + 128]); p1[r] = fast_exp2(p1[r] + relb[i1 + 128]); }
.LBB0_1320:
	s_cmp_lt_i32 s12, s14
	s_cselect_b64 s[0:1], -1, 0
	s_cmp_gt_i32 s12, s10
	s_cselect_b64 s[2:3], -1, 0
	s_or_b64 s[0:1], s[0:1], s[2:3]
	s_and_b64 vcc, exec, s[0:1]
	s_cbranch_vccnz .LBB0_1311
	s_cmp_lt_i32 s12, s15
	s_cbranch_scc1 .Lt2far_2
	v_add_u32_e32 v40, s17, v139
	ds_read_b128 v[32:35], v40
	ds_read_b128 v[36:39], v40 offset:512
	ds_read_b128 v[44:47], v40 offset:2048
	ds_read_b128 v[48:51], v40 offset:2560
	ds_read_b128 v[52:55], v40 offset:4096
	ds_read_b128 v[56:59], v40 offset:4608
	ds_read_b128 v[60:63], v40 offset:6144
	ds_read_b128 v[146:149], v40 offset:6656
	s_mov_b64 s[0:1], -1
	s_cmp_lt_i32 s12, s15
	s_waitcnt vmcnt(5) lgkmcnt(6)
	v_mfma_f32_32x32x16_bf16 v[80:95], v[32:35], v[104:107], 0
	v_mfma_f32_32x32x16_bf16 v[64:79], v[36:39], v[104:107], 0
	s_waitcnt lgkmcnt(4)
	v_mfma_f32_32x32x16_bf16 v[80:95], v[44:47], v[96:99], v[80:95]
	v_mfma_f32_32x32x16_bf16 v[64:79], v[48:51], v[96:99], v[64:79]
	s_waitcnt lgkmcnt(2)
	v_mfma_f32_32x32x16_bf16 v[80:95], v[52:55], v[100:103], v[80:95]
	v_mfma_f32_32x32x16_bf16 v[64:79], v[56:59], v[100:103], v[64:79]
	s_waitcnt vmcnt(4) lgkmcnt(0)
	v_mfma_f32_32x32x16_bf16 v[80:95], v[60:63], v[108:111], v[80:95]
	v_mfma_f32_32x32x16_bf16 v[64:79], v[146:149], v[108:111], v[64:79]
	s_cbranch_scc1 .LBB0_1323
	v_lshl_add_u32 v230, v141, 2, v162
	s_nop 3
	ds_read_b32 v33, v230 offset:236
	ds_read_b32 v40, v230 offset:108
	ds_read_b32 v35, v230 offset:232
	ds_read_b32 v34, v230 offset:104
	ds_read_b32 v37, v230 offset:228
	ds_read_b32 v36, v230 offset:100
	ds_read_b32 v39, v230 offset:224
	ds_read_b32 v38, v230 offset:96
	s_waitcnt lgkmcnt(7)
	v_add_f32_e32 v32, v80, v33
	s_waitcnt lgkmcnt(6)
	v_add_f32_e32 v33, v64, v40
	v_exp_f32_e32 v48, v33
	s_waitcnt lgkmcnt(5)
	v_add_f32_e32 v33, v81, v35
	s_waitcnt lgkmcnt(2)
	v_add_f32_e32 v35, v66, v36
	s_waitcnt lgkmcnt(0)
	v_add_f32_e32 v36, v67, v38
	v_add_f32_e32 v34, v65, v34
	v_exp_f32_e32 v51, v36
	v_exp_f32_e32 v49, v34
	v_add_f32_e32 v34, v82, v37
	v_exp_f32_e32 v50, v35
	v_add_f32_e32 v35, v83, v39
	ds_read_b32 v37, v230 offset:204
	ds_read_b32 v44, v230 offset:76
	ds_read_b32 v39, v230 offset:200
	ds_read_b32 v38, v230 offset:72
	ds_read_b32 v41, v230 offset:196
	ds_read_b32 v40, v230 offset:68
	ds_read_b32 v43, v230 offset:192
	ds_read_b32 v42, v230 offset:64
	s_waitcnt lgkmcnt(7)
	v_add_f32_e32 v36, v84, v37
	s_waitcnt lgkmcnt(6)
	v_add_f32_e32 v37, v68, v44
	v_exp_f32_e32 v52, v37
	s_waitcnt lgkmcnt(5)
	v_add_f32_e32 v37, v85, v39
	s_waitcnt lgkmcnt(2)
	v_add_f32_e32 v39, v70, v40
	s_waitcnt lgkmcnt(0)
	v_add_f32_e32 v40, v71, v42
	v_add_f32_e32 v38, v69, v38
	v_exp_f32_e32 v55, v40
	v_exp_f32_e32 v53, v38
	v_add_f32_e32 v38, v86, v41
	v_exp_f32_e32 v54, v39
	v_add_f32_e32 v39, v87, v43
	ds_read_b32 v41, v230 offset:172
	ds_read_b32 v56, v230 offset:44
	ds_read_b32 v43, v230 offset:168
	ds_read_b32 v42, v230 offset:40
	ds_read_b32 v45, v230 offset:164
	ds_read_b32 v44, v230 offset:36
	ds_read_b32 v47, v230 offset:160
	ds_read_b32 v46, v230 offset:32
	s_waitcnt lgkmcnt(7)
	v_add_f32_e32 v40, v88, v41
	s_waitcnt lgkmcnt(6)
	v_add_f32_e32 v41, v72, v56
	v_exp_f32_e32 v56, v41
	s_waitcnt lgkmcnt(5)
	v_add_f32_e32 v41, v89, v43
	s_waitcnt lgkmcnt(2)
	v_add_f32_e32 v43, v74, v44
	s_waitcnt lgkmcnt(0)
	v_add_f32_e32 v44, v75, v46
	v_add_f32_e32 v42, v73, v42
	v_exp_f32_e32 v59, v44
	v_exp_f32_e32 v57, v42
	v_add_f32_e32 v42, v90, v45
	v_exp_f32_e32 v58, v43
	v_add_f32_e32 v43, v91, v47
	ds_read_b32 v45, v230 offset:140
	ds_read_b32 v142, v230 offset:12
	ds_read_b32 v47, v230 offset:136
	ds_read_b32 v46, v230 offset:8
	ds_read_b32 v143, v230 offset:132
	ds_read_b32 v144, v230 offset:4
	ds_read_b32 v146, v230 offset:128
	ds_read_b32 v63, v230
	s_waitcnt lgkmcnt(7)
	v_add_f32_e32 v44, v92, v45
	s_waitcnt lgkmcnt(6)
	v_add_f32_e32 v45, v76, v142
	v_exp_f32_e32 v60, v45
	s_waitcnt lgkmcnt(5)
	v_add_f32_e32 v45, v93, v47
	s_waitcnt lgkmcnt(4)
	v_add_f32_e32 v46, v77, v46
	s_waitcnt lgkmcnt(2)
	v_add_f32_e32 v47, v78, v144
	v_exp_f32_e32 v61, v46
	v_add_f32_e32 v46, v94, v143
	v_exp_f32_e32 v62, v47
	s_waitcnt lgkmcnt(1)
	v_add_f32_e32 v47, v95, v146
	v_exp_f32_e32 v32, v32
	v_exp_f32_e32 v33, v33
	v_exp_f32_e32 v34, v34
	v_exp_f32_e32 v35, v35
	v_exp_f32_e32 v36, v36
	v_exp_f32_e32 v37, v37
	v_exp_f32_e32 v38, v38
	v_exp_f32_e32 v39, v39
	v_exp_f32_e32 v40, v40
	v_exp_f32_e32 v41, v41
	v_exp_f32_e32 v42, v42
	v_exp_f32_e32 v43, v43
	v_exp_f32_e32 v44, v44
	v_exp_f32_e32 v45, v45
	v_exp_f32_e32 v46, v46
	v_exp_f32_e32 v47, v47
	s_waitcnt lgkmcnt(0)
	v_add_f32_e32 v63, v79, v63
	s_mov_b64 s[0:1], 0
